# K-norm re-read in the proj1 epilogue made coalesced (16 lanes per half-row, DPP row sums) instead of one row per lane
# speedup vs baseline: 1.0093x; 1.0067x over previous
.LBB0_564:
	v_lshl_add_u32 v150, s4, 8, v152
	v_ashrrev_i32_e32 v151, 31, v150
	v_lshl_add_u64 v[144:145], v[150:151], 2, s[16:17]
	s_nop 0
	v_lshl_or_b32 v146, s5, 8, v154
	s_cmp_lt_i32 s5, 8
	v_ashrrev_i32_e32 v147, 31, v146
	s_cselect_b64 vcc, -1, 0
	v_lshlrev_b64 v[148:149], 1, v[146:147]
	v_cndmask_b32_e32 v161, 1.0, v160, vcc
	v_lshlrev_b64 v[164:165], 14, v[150:151]
	v_or_b32_e32 v162, 16, v150
	s_nop 0
	v_fmamk_f32 v146, v242, 0x3a000000, v158
	v_rsq_f32_e32 v252, v146
	s_nop 0
	v_mul_f32_e32 v252, v252, v161
	v_ashrrev_i32_e32 v163, 31, v162
	v_lshl_add_u64 v[146:147], s[10:11], 0, v[164:165]
	v_lshl_add_u64 v[146:147], v[146:147], 0, v[148:149]
	v_lshl_add_u64 v[164:165], v[162:163], 2, s[16:17]
	v_pk_mul_f32 v[126:127], v[126:127], v[252:253] op_sel_hi:[1,0]
	v_pk_mul_f32 v[124:125], v[124:125], v[252:253] op_sel_hi:[1,0]
	v_pk_mul_f32 v[122:123], v[122:123], v[252:253] op_sel_hi:[1,0]
	v_pk_mul_f32 v[120:121], v[120:121], v[252:253] op_sel_hi:[1,0]
	v_pk_mul_f32 v[118:119], v[118:119], v[252:253] op_sel_hi:[1,0]
	v_pk_mul_f32 v[116:117], v[116:117], v[252:253] op_sel_hi:[1,0]
	v_pk_mul_f32 v[168:169], v[114:115], v[252:253] op_sel_hi:[1,0]
	v_pk_mul_f32 v[166:167], v[112:113], v[252:253] op_sel_hi:[1,0]
	v_cvt_pk_bf16_f32 v112, v124, v125
	v_cvt_pk_bf16_f32 v113, v126, v127
	v_cvt_pk_bf16_f32 v114, v120, v121
	v_cvt_pk_bf16_f32 v115, v122, v123
	v_cvt_pk_bf16_f32 v116, v116, v117
	v_cvt_pk_bf16_f32 v117, v118, v119
	v_cvt_pk_bf16_f32 v118, v166, v167
	v_cvt_pk_bf16_f32 v119, v168, v169
	global_store_dwordx4 v[146:147], v[112:115], off
	global_store_dwordx4 v[146:147], v[116:119], off offset:256
	s_nop 0
	v_or_b32_e32 v112, 32, v150
	v_ashrrev_i32_e32 v113, 31, v112
	v_lshl_add_u64 v[116:117], v[112:113], 2, s[16:17]
	s_nop 0
	v_fmamk_f32 v114, v243, 0x3a000000, v158
	v_rsq_f32_e32 v252, v114
	s_nop 0
	v_mul_f32_e32 v252, v252, v161
	v_lshlrev_b64 v[114:115], 14, v[162:163]
	v_lshl_add_u64 v[114:115], s[10:11], 0, v[114:115]
	v_lshl_add_u64 v[114:115], v[114:115], 0, v[148:149]
	v_pk_mul_f32 v[110:111], v[110:111], v[252:253] op_sel_hi:[1,0]
	v_pk_mul_f32 v[108:109], v[108:109], v[252:253] op_sel_hi:[1,0]
	v_pk_mul_f32 v[106:107], v[106:107], v[252:253] op_sel_hi:[1,0]
	v_pk_mul_f32 v[104:105], v[104:105], v[252:253] op_sel_hi:[1,0]
	v_pk_mul_f32 v[102:103], v[102:103], v[252:253] op_sel_hi:[1,0]
	v_pk_mul_f32 v[100:101], v[100:101], v[252:253] op_sel_hi:[1,0]
	v_pk_mul_f32 v[120:121], v[98:99], v[252:253] op_sel_hi:[1,0]
	v_pk_mul_f32 v[118:119], v[96:97], v[252:253] op_sel_hi:[1,0]
	v_cvt_pk_bf16_f32 v96, v108, v109
	v_cvt_pk_bf16_f32 v97, v110, v111
	v_cvt_pk_bf16_f32 v98, v104, v105
	v_cvt_pk_bf16_f32 v99, v106, v107
	v_cvt_pk_bf16_f32 v100, v100, v101
	v_cvt_pk_bf16_f32 v101, v102, v103
	v_cvt_pk_bf16_f32 v102, v118, v119
	v_cvt_pk_bf16_f32 v103, v120, v121
	global_store_dwordx4 v[114:115], v[96:99], off
	global_store_dwordx4 v[114:115], v[100:103], off offset:256
	s_nop 0
	v_or_b32_e32 v96, 48, v150
	v_ashrrev_i32_e32 v97, 31, v96
	v_lshl_add_u64 v[100:101], v[96:97], 2, s[16:17]
	s_nop 0
	v_fmamk_f32 v98, v244, 0x3a000000, v158
	v_rsq_f32_e32 v252, v98
	s_nop 0
	v_mul_f32_e32 v252, v252, v161
	v_lshlrev_b64 v[98:99], 14, v[112:113]
	v_lshl_add_u64 v[98:99], s[10:11], 0, v[98:99]
	v_lshl_add_u64 v[98:99], v[98:99], 0, v[148:149]
	v_pk_mul_f32 v[94:95], v[94:95], v[252:253] op_sel_hi:[1,0]
	v_pk_mul_f32 v[92:93], v[92:93], v[252:253] op_sel_hi:[1,0]
	v_pk_mul_f32 v[90:91], v[90:91], v[252:253] op_sel_hi:[1,0]
	v_pk_mul_f32 v[88:89], v[88:89], v[252:253] op_sel_hi:[1,0]
	v_pk_mul_f32 v[86:87], v[86:87], v[252:253] op_sel_hi:[1,0]
	v_pk_mul_f32 v[84:85], v[84:85], v[252:253] op_sel_hi:[1,0]
	v_pk_mul_f32 v[104:105], v[82:83], v[252:253] op_sel_hi:[1,0]
	v_pk_mul_f32 v[102:103], v[80:81], v[252:253] op_sel_hi:[1,0]
	v_cvt_pk_bf16_f32 v80, v92, v93
	v_cvt_pk_bf16_f32 v81, v94, v95
	v_cvt_pk_bf16_f32 v82, v88, v89
	v_cvt_pk_bf16_f32 v83, v90, v91
	v_cvt_pk_bf16_f32 v84, v84, v85
	v_cvt_pk_bf16_f32 v85, v86, v87
	v_cvt_pk_bf16_f32 v86, v102, v103
	v_cvt_pk_bf16_f32 v87, v104, v105
	global_store_dwordx4 v[98:99], v[80:83], off
	global_store_dwordx4 v[98:99], v[84:87], off offset:256
	s_nop 0
	s_nop 0
	v_fmamk_f32 v80, v245, 0x3a000000, v158
	v_rsq_f32_e32 v252, v80
	s_nop 0
	v_mul_f32_e32 v252, v252, v161
	v_lshlrev_b64 v[80:81], 14, v[96:97]
	v_lshl_add_u64 v[80:81], s[10:11], 0, v[80:81]
	v_lshl_add_u64 v[80:81], v[80:81], 0, v[148:149]
	v_pk_mul_f32 v[78:79], v[78:79], v[252:253] op_sel_hi:[1,0]
	v_pk_mul_f32 v[76:77], v[76:77], v[252:253] op_sel_hi:[1,0]
	v_pk_mul_f32 v[74:75], v[74:75], v[252:253] op_sel_hi:[1,0]
	v_pk_mul_f32 v[72:73], v[72:73], v[252:253] op_sel_hi:[1,0]
	v_pk_mul_f32 v[70:71], v[70:71], v[252:253] op_sel_hi:[1,0]
	v_pk_mul_f32 v[68:69], v[68:69], v[252:253] op_sel_hi:[1,0]
	v_pk_mul_f32 v[84:85], v[66:67], v[252:253] op_sel_hi:[1,0]
	v_pk_mul_f32 v[82:83], v[64:65], v[252:253] op_sel_hi:[1,0]
	v_cvt_pk_bf16_f32 v64, v76, v77
	v_cvt_pk_bf16_f32 v65, v78, v79
	v_cvt_pk_bf16_f32 v66, v72, v73
	v_cvt_pk_bf16_f32 v67, v74, v75
	v_cvt_pk_bf16_f32 v68, v68, v69
	v_cvt_pk_bf16_f32 v69, v70, v71
	v_cvt_pk_bf16_f32 v70, v82, v83
	v_cvt_pk_bf16_f32 v71, v84, v85
	global_store_dwordx4 v[80:81], v[64:67], off
	global_store_dwordx4 v[80:81], v[68:71], off offset:256
	s_nop 0
	s_nop 0
	v_fmamk_f32 v64, v246, 0x3a000000, v158
	v_rsq_f32_e32 v252, v64
	s_nop 0
	v_mul_f32_e32 v252, v252, v161
	v_lshl_add_u64 v[64:65], v[146:147], 0, s[20:21]
	v_add_co_u32_e32 v66, vcc, s75, v146
	v_addc_co_u32_e32 v67, vcc, 0, v147, vcc
	v_pk_mul_f32 v[62:63], v[62:63], v[252:253] op_sel_hi:[1,0]
	v_pk_mul_f32 v[60:61], v[60:61], v[252:253] op_sel_hi:[1,0]
	v_pk_mul_f32 v[58:59], v[58:59], v[252:253] op_sel_hi:[1,0]
	v_pk_mul_f32 v[56:57], v[56:57], v[252:253] op_sel_hi:[1,0]
	v_pk_mul_f32 v[54:55], v[54:55], v[252:253] op_sel_hi:[1,0]
	v_pk_mul_f32 v[52:53], v[52:53], v[252:253] op_sel_hi:[1,0]
	v_pk_mul_f32 v[70:71], v[50:51], v[252:253] op_sel_hi:[1,0]
	v_pk_mul_f32 v[68:69], v[48:49], v[252:253] op_sel_hi:[1,0]
	v_cvt_pk_bf16_f32 v48, v60, v61
	v_cvt_pk_bf16_f32 v49, v62, v63
	v_cvt_pk_bf16_f32 v50, v56, v57
	v_cvt_pk_bf16_f32 v51, v58, v59
	v_cvt_pk_bf16_f32 v52, v52, v53
	v_cvt_pk_bf16_f32 v53, v54, v55
	v_cvt_pk_bf16_f32 v54, v68, v69
	v_cvt_pk_bf16_f32 v55, v70, v71
	global_store_dwordx4 v[66:67], v[48:51], off
	global_store_dwordx4 v[64:65], v[52:55], off offset:256
	s_nop 0
	s_nop 0
	v_fmamk_f32 v48, v247, 0x3a000000, v158
	v_rsq_f32_e32 v252, v48
	s_nop 0
	v_mul_f32_e32 v252, v252, v161
	v_lshl_add_u64 v[48:49], v[146:147], 0, s[22:23]
	v_add_co_u32_e32 v50, vcc, s76, v146
	v_addc_co_u32_e32 v51, vcc, 0, v147, vcc
	v_pk_mul_f32 v[46:47], v[46:47], v[252:253] op_sel_hi:[1,0]
	v_pk_mul_f32 v[44:45], v[44:45], v[252:253] op_sel_hi:[1,0]
	v_pk_mul_f32 v[42:43], v[42:43], v[252:253] op_sel_hi:[1,0]
	v_pk_mul_f32 v[40:41], v[40:41], v[252:253] op_sel_hi:[1,0]
	v_pk_mul_f32 v[38:39], v[38:39], v[252:253] op_sel_hi:[1,0]
	v_pk_mul_f32 v[36:37], v[36:37], v[252:253] op_sel_hi:[1,0]
	v_pk_mul_f32 v[54:55], v[34:35], v[252:253] op_sel_hi:[1,0]
	v_pk_mul_f32 v[52:53], v[32:33], v[252:253] op_sel_hi:[1,0]
	v_cvt_pk_bf16_f32 v32, v44, v45
	v_cvt_pk_bf16_f32 v33, v46, v47
	v_cvt_pk_bf16_f32 v34, v40, v41
	v_cvt_pk_bf16_f32 v35, v42, v43
	v_cvt_pk_bf16_f32 v36, v36, v37
	v_cvt_pk_bf16_f32 v37, v38, v39
	v_cvt_pk_bf16_f32 v38, v52, v53
	v_cvt_pk_bf16_f32 v39, v54, v55
	global_store_dwordx4 v[50:51], v[32:35], off
	global_store_dwordx4 v[48:49], v[36:39], off offset:256
	s_nop 0
	s_nop 0
	v_fmamk_f32 v32, v248, 0x3a000000, v158
	v_rsq_f32_e32 v252, v32
	s_nop 0
	v_mul_f32_e32 v252, v252, v161
	v_lshl_add_u64 v[32:33], v[146:147], 0, s[24:25]
	v_add_co_u32_e32 v34, vcc, s77, v146
	v_addc_co_u32_e32 v35, vcc, 0, v147, vcc
	v_pk_mul_f32 v[30:31], v[30:31], v[252:253] op_sel_hi:[1,0]
	v_pk_mul_f32 v[28:29], v[28:29], v[252:253] op_sel_hi:[1,0]
	v_pk_mul_f32 v[26:27], v[26:27], v[252:253] op_sel_hi:[1,0]
	v_pk_mul_f32 v[24:25], v[24:25], v[252:253] op_sel_hi:[1,0]
	v_pk_mul_f32 v[22:23], v[22:23], v[252:253] op_sel_hi:[1,0]
	v_pk_mul_f32 v[20:21], v[20:21], v[252:253] op_sel_hi:[1,0]
	v_pk_mul_f32 v[38:39], v[18:19], v[252:253] op_sel_hi:[1,0]
	v_pk_mul_f32 v[36:37], v[16:17], v[252:253] op_sel_hi:[1,0]
	v_cvt_pk_bf16_f32 v16, v28, v29
	v_cvt_pk_bf16_f32 v17, v30, v31
	v_cvt_pk_bf16_f32 v18, v24, v25
	v_cvt_pk_bf16_f32 v19, v26, v27
	v_cvt_pk_bf16_f32 v20, v20, v21
	v_cvt_pk_bf16_f32 v21, v22, v23
	v_cvt_pk_bf16_f32 v22, v36, v37
	v_cvt_pk_bf16_f32 v23, v38, v39
	global_store_dwordx4 v[34:35], v[16:19], off
	global_store_dwordx4 v[32:33], v[20:23], off offset:256
	s_nop 0
	s_nop 0
	v_fmamk_f32 v16, v249, 0x3a000000, v158
	v_rsq_f32_e32 v252, v16
	s_nop 0
	v_mul_f32_e32 v252, v252, v161
	v_lshl_add_u64 v[16:17], v[146:147], 0, s[26:27]
	v_add_co_u32_e32 v18, vcc, s78, v146
	v_addc_co_u32_e32 v19, vcc, 0, v147, vcc
	v_pk_mul_f32 v[14:15], v[14:15], v[252:253] op_sel_hi:[1,0]
	v_pk_mul_f32 v[12:13], v[12:13], v[252:253] op_sel_hi:[1,0]
	v_pk_mul_f32 v[10:11], v[10:11], v[252:253] op_sel_hi:[1,0]
	v_pk_mul_f32 v[8:9], v[8:9], v[252:253] op_sel_hi:[1,0]
	s_andn2_b64 vcc, exec, s[0:1]
	v_pk_mul_f32 v[6:7], v[6:7], v[252:253] op_sel_hi:[1,0]
	v_pk_mul_f32 v[4:5], v[4:5], v[252:253] op_sel_hi:[1,0]
	v_pk_mul_f32 v[22:23], v[2:3], v[252:253] op_sel_hi:[1,0]
	v_pk_mul_f32 v[20:21], v[0:1], v[252:253] op_sel_hi:[1,0]
	v_cvt_pk_bf16_f32 v0, v12, v13
	v_cvt_pk_bf16_f32 v1, v14, v15
	v_cvt_pk_bf16_f32 v2, v8, v9
	v_cvt_pk_bf16_f32 v3, v10, v11
	s_mov_b64 s[0:1], -1
	v_cvt_pk_bf16_f32 v4, v4, v5
	v_cvt_pk_bf16_f32 v5, v6, v7
	v_cvt_pk_bf16_f32 v6, v20, v21
	v_cvt_pk_bf16_f32 v7, v22, v23
	global_store_dwordx4 v[18:19], v[0:3], off
	global_store_dwordx4 v[16:17], v[4:7], off offset:256
	s_mov_b64 s[96:97], vcc
	s_cmp_lt_i32 s5, 8
	s_cbranch_scc1 .Lkn_skip
	s_cmp_gt_i32 s5, 15
	s_cbranch_scc1 .Lkn_skip
	s_waitcnt vmcnt(0)
	s_barrier
	v_lshrrev_b32_e32 v0, 6, v255
	v_and_b32_e32 v0, 3, v0
	v_lshlrev_b32_e32 v0, 6, v0
	v_bfe_u32 v1, v255, 4, 2
	v_add_u32_e32 v0, v0, v1
	s_lshl_b32 s89, s4, 8
	v_add_u32_e32 v0, s89, v0
	v_lshlrev_b32_e32 v0, 14, v0
	v_lshrrev_b32_e32 v1, 8, v255
	v_lshlrev_b32_e32 v1, 8, v1
	v_and_b32_e32 v2, 15, v255
	v_lshl_add_u32 v1, v2, 4, v1
	s_lshl_b32 s89, s5, 9
	v_add3_u32 v0, v0, v1, s89
	global_load_dwordx4 v[2:5], v0, s[10:11] sc1
	v_add_u32_e32 v0, 0x10000, v0
	global_load_dwordx4 v[6:9], v0, s[10:11] sc1
	v_add_u32_e32 v0, 0x10000, v0
	global_load_dwordx4 v[10:13], v0, s[10:11] sc1
	v_add_u32_e32 v0, 0x10000, v0
	global_load_dwordx4 v[14:17], v0, s[10:11] sc1
	v_add_u32_e32 v0, 0x10000, v0
	global_load_dwordx4 v[18:21], v0, s[10:11] sc1
	v_add_u32_e32 v0, 0x10000, v0
	global_load_dwordx4 v[22:25], v0, s[10:11] sc1
	v_add_u32_e32 v0, 0x10000, v0
	global_load_dwordx4 v[26:29], v0, s[10:11] sc1
	v_add_u32_e32 v0, 0x10000, v0
	global_load_dwordx4 v[30:33], v0, s[10:11] sc1
	v_add_u32_e32 v0, 0x10000, v0
	global_load_dwordx4 v[34:37], v0, s[10:11] sc1
	v_add_u32_e32 v0, 0x10000, v0
	global_load_dwordx4 v[38:41], v0, s[10:11] sc1
	v_add_u32_e32 v0, 0x10000, v0
	global_load_dwordx4 v[42:45], v0, s[10:11] sc1
	v_add_u32_e32 v0, 0x10000, v0
	global_load_dwordx4 v[46:49], v0, s[10:11] sc1
	v_add_u32_e32 v0, 0x10000, v0
	global_load_dwordx4 v[50:53], v0, s[10:11] sc1
	v_add_u32_e32 v0, 0x10000, v0
	global_load_dwordx4 v[54:57], v0, s[10:11] sc1
	v_add_u32_e32 v0, 0x10000, v0
	global_load_dwordx4 v[58:61], v0, s[10:11] sc1
	v_add_u32_e32 v0, 0x10000, v0
	global_load_dwordx4 v[62:65], v0, s[10:11] sc1
	v_mov_b32_e32 v69, 0
	s_waitcnt vmcnt(15)
	v_lshlrev_b32_e32 v67, 16, v2
	v_and_b32_e32 v68, 0xffff0000, v2
	v_mul_f32_e32 v66, v67, v67
	v_fmac_f32_e32 v66, v68, v68
	v_lshlrev_b32_e32 v67, 16, v3
	v_and_b32_e32 v68, 0xffff0000, v3
	v_fmac_f32_e32 v66, v67, v67
	v_fmac_f32_e32 v66, v68, v68
	v_lshlrev_b32_e32 v67, 16, v4
	v_and_b32_e32 v68, 0xffff0000, v4
	v_fmac_f32_e32 v66, v67, v67
	v_fmac_f32_e32 v66, v68, v68
	v_lshlrev_b32_e32 v67, 16, v5
	v_and_b32_e32 v68, 0xffff0000, v5
	v_fmac_f32_e32 v66, v67, v67
	v_fmac_f32_e32 v66, v68, v68
	s_nop 1
	v_add_f32_dpp v66, v66, v66 row_ror:8 row_mask:0xf bank_mask:0xf
	s_nop 1
	v_add_f32_dpp v66, v66, v66 row_ror:4 row_mask:0xf bank_mask:0xf
	s_nop 1
	v_add_f32_dpp v66, v66, v66 row_ror:2 row_mask:0xf bank_mask:0xf
	s_nop 1
	v_add_f32_dpp v66, v66, v66 row_ror:1 row_mask:0xf bank_mask:0xf
	v_max_f32_e32 v69, v69, v66
	s_waitcnt vmcnt(14)
	v_lshlrev_b32_e32 v67, 16, v6
	v_and_b32_e32 v68, 0xffff0000, v6
	v_mul_f32_e32 v66, v67, v67
	v_fmac_f32_e32 v66, v68, v68
	v_lshlrev_b32_e32 v67, 16, v7
	v_and_b32_e32 v68, 0xffff0000, v7
	v_fmac_f32_e32 v66, v67, v67
	v_fmac_f32_e32 v66, v68, v68
	v_lshlrev_b32_e32 v67, 16, v8
	v_and_b32_e32 v68, 0xffff0000, v8
	v_fmac_f32_e32 v66, v67, v67
	v_fmac_f32_e32 v66, v68, v68
	v_lshlrev_b32_e32 v67, 16, v9
	v_and_b32_e32 v68, 0xffff0000, v9
	v_fmac_f32_e32 v66, v67, v67
	v_fmac_f32_e32 v66, v68, v68
	s_nop 1
	v_add_f32_dpp v66, v66, v66 row_ror:8 row_mask:0xf bank_mask:0xf
	s_nop 1
	v_add_f32_dpp v66, v66, v66 row_ror:4 row_mask:0xf bank_mask:0xf
	s_nop 1
	v_add_f32_dpp v66, v66, v66 row_ror:2 row_mask:0xf bank_mask:0xf
	s_nop 1
	v_add_f32_dpp v66, v66, v66 row_ror:1 row_mask:0xf bank_mask:0xf
	v_max_f32_e32 v69, v69, v66
	s_waitcnt vmcnt(13)
	v_lshlrev_b32_e32 v67, 16, v10
	v_and_b32_e32 v68, 0xffff0000, v10
	v_mul_f32_e32 v66, v67, v67
	v_fmac_f32_e32 v66, v68, v68
	v_lshlrev_b32_e32 v67, 16, v11
	v_and_b32_e32 v68, 0xffff0000, v11
	v_fmac_f32_e32 v66, v67, v67
	v_fmac_f32_e32 v66, v68, v68
	v_lshlrev_b32_e32 v67, 16, v12
	v_and_b32_e32 v68, 0xffff0000, v12
	v_fmac_f32_e32 v66, v67, v67
	v_fmac_f32_e32 v66, v68, v68
	v_lshlrev_b32_e32 v67, 16, v13
	v_and_b32_e32 v68, 0xffff0000, v13
	v_fmac_f32_e32 v66, v67, v67
	v_fmac_f32_e32 v66, v68, v68
	s_nop 1
	v_add_f32_dpp v66, v66, v66 row_ror:8 row_mask:0xf bank_mask:0xf
	s_nop 1
	v_add_f32_dpp v66, v66, v66 row_ror:4 row_mask:0xf bank_mask:0xf
	s_nop 1
	v_add_f32_dpp v66, v66, v66 row_ror:2 row_mask:0xf bank_mask:0xf
	s_nop 1
	v_add_f32_dpp v66, v66, v66 row_ror:1 row_mask:0xf bank_mask:0xf
	v_max_f32_e32 v69, v69, v66
	s_waitcnt vmcnt(12)
	v_lshlrev_b32_e32 v67, 16, v14
	v_and_b32_e32 v68, 0xffff0000, v14
	v_mul_f32_e32 v66, v67, v67
	v_fmac_f32_e32 v66, v68, v68
	v_lshlrev_b32_e32 v67, 16, v15
	v_and_b32_e32 v68, 0xffff0000, v15
	v_fmac_f32_e32 v66, v67, v67
	v_fmac_f32_e32 v66, v68, v68
	v_lshlrev_b32_e32 v67, 16, v16
	v_and_b32_e32 v68, 0xffff0000, v16
	v_fmac_f32_e32 v66, v67, v67
	v_fmac_f32_e32 v66, v68, v68
	v_lshlrev_b32_e32 v67, 16, v17
	v_and_b32_e32 v68, 0xffff0000, v17
	v_fmac_f32_e32 v66, v67, v67
	v_fmac_f32_e32 v66, v68, v68
	s_nop 1
	v_add_f32_dpp v66, v66, v66 row_ror:8 row_mask:0xf bank_mask:0xf
	s_nop 1
	v_add_f32_dpp v66, v66, v66 row_ror:4 row_mask:0xf bank_mask:0xf
	s_nop 1
	v_add_f32_dpp v66, v66, v66 row_ror:2 row_mask:0xf bank_mask:0xf
	s_nop 1
	v_add_f32_dpp v66, v66, v66 row_ror:1 row_mask:0xf bank_mask:0xf
	v_max_f32_e32 v69, v69, v66
	s_waitcnt vmcnt(11)
	v_lshlrev_b32_e32 v67, 16, v18
	v_and_b32_e32 v68, 0xffff0000, v18
	v_mul_f32_e32 v66, v67, v67
	v_fmac_f32_e32 v66, v68, v68
	v_lshlrev_b32_e32 v67, 16, v19
	v_and_b32_e32 v68, 0xffff0000, v19
	v_fmac_f32_e32 v66, v67, v67
	v_fmac_f32_e32 v66, v68, v68
	v_lshlrev_b32_e32 v67, 16, v20
	v_and_b32_e32 v68, 0xffff0000, v20
	v_fmac_f32_e32 v66, v67, v67
	v_fmac_f32_e32 v66, v68, v68
	v_lshlrev_b32_e32 v67, 16, v21
	v_and_b32_e32 v68, 0xffff0000, v21
	v_fmac_f32_e32 v66, v67, v67
	v_fmac_f32_e32 v66, v68, v68
	s_nop 1
	v_add_f32_dpp v66, v66, v66 row_ror:8 row_mask:0xf bank_mask:0xf
	s_nop 1
	v_add_f32_dpp v66, v66, v66 row_ror:4 row_mask:0xf bank_mask:0xf
	s_nop 1
	v_add_f32_dpp v66, v66, v66 row_ror:2 row_mask:0xf bank_mask:0xf
	s_nop 1
	v_add_f32_dpp v66, v66, v66 row_ror:1 row_mask:0xf bank_mask:0xf
	v_max_f32_e32 v69, v69, v66
	s_waitcnt vmcnt(10)
	v_lshlrev_b32_e32 v67, 16, v22
	v_and_b32_e32 v68, 0xffff0000, v22
	v_mul_f32_e32 v66, v67, v67
	v_fmac_f32_e32 v66, v68, v68
	v_lshlrev_b32_e32 v67, 16, v23
	v_and_b32_e32 v68, 0xffff0000, v23
	v_fmac_f32_e32 v66, v67, v67
	v_fmac_f32_e32 v66, v68, v68
	v_lshlrev_b32_e32 v67, 16, v24
	v_and_b32_e32 v68, 0xffff0000, v24
	v_fmac_f32_e32 v66, v67, v67
	v_fmac_f32_e32 v66, v68, v68
	v_lshlrev_b32_e32 v67, 16, v25
	v_and_b32_e32 v68, 0xffff0000, v25
	v_fmac_f32_e32 v66, v67, v67
	v_fmac_f32_e32 v66, v68, v68
	s_nop 1
	v_add_f32_dpp v66, v66, v66 row_ror:8 row_mask:0xf bank_mask:0xf
	s_nop 1
	v_add_f32_dpp v66, v66, v66 row_ror:4 row_mask:0xf bank_mask:0xf
	s_nop 1
	v_add_f32_dpp v66, v66, v66 row_ror:2 row_mask:0xf bank_mask:0xf
	s_nop 1
	v_add_f32_dpp v66, v66, v66 row_ror:1 row_mask:0xf bank_mask:0xf
	v_max_f32_e32 v69, v69, v66
	s_waitcnt vmcnt(9)
	v_lshlrev_b32_e32 v67, 16, v26
	v_and_b32_e32 v68, 0xffff0000, v26
	v_mul_f32_e32 v66, v67, v67
	v_fmac_f32_e32 v66, v68, v68
	v_lshlrev_b32_e32 v67, 16, v27
	v_and_b32_e32 v68, 0xffff0000, v27
	v_fmac_f32_e32 v66, v67, v67
	v_fmac_f32_e32 v66, v68, v68
	v_lshlrev_b32_e32 v67, 16, v28
	v_and_b32_e32 v68, 0xffff0000, v28
	v_fmac_f32_e32 v66, v67, v67
	v_fmac_f32_e32 v66, v68, v68
	v_lshlrev_b32_e32 v67, 16, v29
	v_and_b32_e32 v68, 0xffff0000, v29
	v_fmac_f32_e32 v66, v67, v67
	v_fmac_f32_e32 v66, v68, v68
	s_nop 1
	v_add_f32_dpp v66, v66, v66 row_ror:8 row_mask:0xf bank_mask:0xf
	s_nop 1
	v_add_f32_dpp v66, v66, v66 row_ror:4 row_mask:0xf bank_mask:0xf
	s_nop 1
	v_add_f32_dpp v66, v66, v66 row_ror:2 row_mask:0xf bank_mask:0xf
	s_nop 1
	v_add_f32_dpp v66, v66, v66 row_ror:1 row_mask:0xf bank_mask:0xf
	v_max_f32_e32 v69, v69, v66
	s_waitcnt vmcnt(8)
	v_lshlrev_b32_e32 v67, 16, v30
	v_and_b32_e32 v68, 0xffff0000, v30
	v_mul_f32_e32 v66, v67, v67
	v_fmac_f32_e32 v66, v68, v68
	v_lshlrev_b32_e32 v67, 16, v31
	v_and_b32_e32 v68, 0xffff0000, v31
	v_fmac_f32_e32 v66, v67, v67
	v_fmac_f32_e32 v66, v68, v68
	v_lshlrev_b32_e32 v67, 16, v32
	v_and_b32_e32 v68, 0xffff0000, v32
	v_fmac_f32_e32 v66, v67, v67
	v_fmac_f32_e32 v66, v68, v68
	v_lshlrev_b32_e32 v67, 16, v33
	v_and_b32_e32 v68, 0xffff0000, v33
	v_fmac_f32_e32 v66, v67, v67
	v_fmac_f32_e32 v66, v68, v68
	s_nop 1
	v_add_f32_dpp v66, v66, v66 row_ror:8 row_mask:0xf bank_mask:0xf
	s_nop 1
	v_add_f32_dpp v66, v66, v66 row_ror:4 row_mask:0xf bank_mask:0xf
	s_nop 1
	v_add_f32_dpp v66, v66, v66 row_ror:2 row_mask:0xf bank_mask:0xf
	s_nop 1
	v_add_f32_dpp v66, v66, v66 row_ror:1 row_mask:0xf bank_mask:0xf
	v_max_f32_e32 v69, v69, v66
	s_waitcnt vmcnt(7)
	v_lshlrev_b32_e32 v67, 16, v34
	v_and_b32_e32 v68, 0xffff0000, v34
	v_mul_f32_e32 v66, v67, v67
	v_fmac_f32_e32 v66, v68, v68
	v_lshlrev_b32_e32 v67, 16, v35
	v_and_b32_e32 v68, 0xffff0000, v35
	v_fmac_f32_e32 v66, v67, v67
	v_fmac_f32_e32 v66, v68, v68
	v_lshlrev_b32_e32 v67, 16, v36
	v_and_b32_e32 v68, 0xffff0000, v36
	v_fmac_f32_e32 v66, v67, v67
	v_fmac_f32_e32 v66, v68, v68
	v_lshlrev_b32_e32 v67, 16, v37
	v_and_b32_e32 v68, 0xffff0000, v37
	v_fmac_f32_e32 v66, v67, v67
	v_fmac_f32_e32 v66, v68, v68
	s_nop 1
	v_add_f32_dpp v66, v66, v66 row_ror:8 row_mask:0xf bank_mask:0xf
	s_nop 1
	v_add_f32_dpp v66, v66, v66 row_ror:4 row_mask:0xf bank_mask:0xf
	s_nop 1
	v_add_f32_dpp v66, v66, v66 row_ror:2 row_mask:0xf bank_mask:0xf
	s_nop 1
	v_add_f32_dpp v66, v66, v66 row_ror:1 row_mask:0xf bank_mask:0xf
	v_max_f32_e32 v69, v69, v66
	s_waitcnt vmcnt(6)
	v_lshlrev_b32_e32 v67, 16, v38
	v_and_b32_e32 v68, 0xffff0000, v38
	v_mul_f32_e32 v66, v67, v67
	v_fmac_f32_e32 v66, v68, v68
	v_lshlrev_b32_e32 v67, 16, v39
	v_and_b32_e32 v68, 0xffff0000, v39
	v_fmac_f32_e32 v66, v67, v67
	v_fmac_f32_e32 v66, v68, v68
	v_lshlrev_b32_e32 v67, 16, v40
	v_and_b32_e32 v68, 0xffff0000, v40
	v_fmac_f32_e32 v66, v67, v67
	v_fmac_f32_e32 v66, v68, v68
	v_lshlrev_b32_e32 v67, 16, v41
	v_and_b32_e32 v68, 0xffff0000, v41
	v_fmac_f32_e32 v66, v67, v67
	v_fmac_f32_e32 v66, v68, v68
	s_nop 1
	v_add_f32_dpp v66, v66, v66 row_ror:8 row_mask:0xf bank_mask:0xf
	s_nop 1
	v_add_f32_dpp v66, v66, v66 row_ror:4 row_mask:0xf bank_mask:0xf
	s_nop 1
	v_add_f32_dpp v66, v66, v66 row_ror:2 row_mask:0xf bank_mask:0xf
	s_nop 1
	v_add_f32_dpp v66, v66, v66 row_ror:1 row_mask:0xf bank_mask:0xf
	v_max_f32_e32 v69, v69, v66
	s_waitcnt vmcnt(5)
	v_lshlrev_b32_e32 v67, 16, v42
	v_and_b32_e32 v68, 0xffff0000, v42
	v_mul_f32_e32 v66, v67, v67
	v_fmac_f32_e32 v66, v68, v68
	v_lshlrev_b32_e32 v67, 16, v43
	v_and_b32_e32 v68, 0xffff0000, v43
	v_fmac_f32_e32 v66, v67, v67
	v_fmac_f32_e32 v66, v68, v68
	v_lshlrev_b32_e32 v67, 16, v44
	v_and_b32_e32 v68, 0xffff0000, v44
	v_fmac_f32_e32 v66, v67, v67
	v_fmac_f32_e32 v66, v68, v68
	v_lshlrev_b32_e32 v67, 16, v45
	v_and_b32_e32 v68, 0xffff0000, v45
	v_fmac_f32_e32 v66, v67, v67
	v_fmac_f32_e32 v66, v68, v68
	s_nop 1
	v_add_f32_dpp v66, v66, v66 row_ror:8 row_mask:0xf bank_mask:0xf
	s_nop 1
	v_add_f32_dpp v66, v66, v66 row_ror:4 row_mask:0xf bank_mask:0xf
	s_nop 1
	v_add_f32_dpp v66, v66, v66 row_ror:2 row_mask:0xf bank_mask:0xf
	s_nop 1
	v_add_f32_dpp v66, v66, v66 row_ror:1 row_mask:0xf bank_mask:0xf
	v_max_f32_e32 v69, v69, v66
	s_waitcnt vmcnt(4)
	v_lshlrev_b32_e32 v67, 16, v46
	v_and_b32_e32 v68, 0xffff0000, v46
	v_mul_f32_e32 v66, v67, v67
	v_fmac_f32_e32 v66, v68, v68
	v_lshlrev_b32_e32 v67, 16, v47
	v_and_b32_e32 v68, 0xffff0000, v47
	v_fmac_f32_e32 v66, v67, v67
	v_fmac_f32_e32 v66, v68, v68
	v_lshlrev_b32_e32 v67, 16, v48
	v_and_b32_e32 v68, 0xffff0000, v48
	v_fmac_f32_e32 v66, v67, v67
	v_fmac_f32_e32 v66, v68, v68
	v_lshlrev_b32_e32 v67, 16, v49
	v_and_b32_e32 v68, 0xffff0000, v49
	v_fmac_f32_e32 v66, v67, v67
	v_fmac_f32_e32 v66, v68, v68
	s_nop 1
	v_add_f32_dpp v66, v66, v66 row_ror:8 row_mask:0xf bank_mask:0xf
	s_nop 1
	v_add_f32_dpp v66, v66, v66 row_ror:4 row_mask:0xf bank_mask:0xf
	s_nop 1
	v_add_f32_dpp v66, v66, v66 row_ror:2 row_mask:0xf bank_mask:0xf
	s_nop 1
	v_add_f32_dpp v66, v66, v66 row_ror:1 row_mask:0xf bank_mask:0xf
	v_max_f32_e32 v69, v69, v66
	s_waitcnt vmcnt(3)
	v_lshlrev_b32_e32 v67, 16, v50
	v_and_b32_e32 v68, 0xffff0000, v50
	v_mul_f32_e32 v66, v67, v67
	v_fmac_f32_e32 v66, v68, v68
	v_lshlrev_b32_e32 v67, 16, v51
	v_and_b32_e32 v68, 0xffff0000, v51
	v_fmac_f32_e32 v66, v67, v67
	v_fmac_f32_e32 v66, v68, v68
	v_lshlrev_b32_e32 v67, 16, v52
	v_and_b32_e32 v68, 0xffff0000, v52
	v_fmac_f32_e32 v66, v67, v67
	v_fmac_f32_e32 v66, v68, v68
	v_lshlrev_b32_e32 v67, 16, v53
	v_and_b32_e32 v68, 0xffff0000, v53
	v_fmac_f32_e32 v66, v67, v67
	v_fmac_f32_e32 v66, v68, v68
	s_nop 1
	v_add_f32_dpp v66, v66, v66 row_ror:8 row_mask:0xf bank_mask:0xf
	s_nop 1
	v_add_f32_dpp v66, v66, v66 row_ror:4 row_mask:0xf bank_mask:0xf
	s_nop 1
	v_add_f32_dpp v66, v66, v66 row_ror:2 row_mask:0xf bank_mask:0xf
	s_nop 1
	v_add_f32_dpp v66, v66, v66 row_ror:1 row_mask:0xf bank_mask:0xf
	v_max_f32_e32 v69, v69, v66
	s_waitcnt vmcnt(2)
	v_lshlrev_b32_e32 v67, 16, v54
	v_and_b32_e32 v68, 0xffff0000, v54
	v_mul_f32_e32 v66, v67, v67
	v_fmac_f32_e32 v66, v68, v68
	v_lshlrev_b32_e32 v67, 16, v55
	v_and_b32_e32 v68, 0xffff0000, v55
	v_fmac_f32_e32 v66, v67, v67
	v_fmac_f32_e32 v66, v68, v68
	v_lshlrev_b32_e32 v67, 16, v56
	v_and_b32_e32 v68, 0xffff0000, v56
	v_fmac_f32_e32 v66, v67, v67
	v_fmac_f32_e32 v66, v68, v68
	v_lshlrev_b32_e32 v67, 16, v57
	v_and_b32_e32 v68, 0xffff0000, v57
	v_fmac_f32_e32 v66, v67, v67
	v_fmac_f32_e32 v66, v68, v68
	s_nop 1
	v_add_f32_dpp v66, v66, v66 row_ror:8 row_mask:0xf bank_mask:0xf
	s_nop 1
	v_add_f32_dpp v66, v66, v66 row_ror:4 row_mask:0xf bank_mask:0xf
	s_nop 1
	v_add_f32_dpp v66, v66, v66 row_ror:2 row_mask:0xf bank_mask:0xf
	s_nop 1
	v_add_f32_dpp v66, v66, v66 row_ror:1 row_mask:0xf bank_mask:0xf
	v_max_f32_e32 v69, v69, v66
	s_waitcnt vmcnt(1)
	v_lshlrev_b32_e32 v67, 16, v58
	v_and_b32_e32 v68, 0xffff0000, v58
	v_mul_f32_e32 v66, v67, v67
	v_fmac_f32_e32 v66, v68, v68
	v_lshlrev_b32_e32 v67, 16, v59
	v_and_b32_e32 v68, 0xffff0000, v59
	v_fmac_f32_e32 v66, v67, v67
	v_fmac_f32_e32 v66, v68, v68
	v_lshlrev_b32_e32 v67, 16, v60
	v_and_b32_e32 v68, 0xffff0000, v60
	v_fmac_f32_e32 v66, v67, v67
	v_fmac_f32_e32 v66, v68, v68
	v_lshlrev_b32_e32 v67, 16, v61
	v_and_b32_e32 v68, 0xffff0000, v61
	v_fmac_f32_e32 v66, v67, v67
	v_fmac_f32_e32 v66, v68, v68
	s_nop 1
	v_add_f32_dpp v66, v66, v66 row_ror:8 row_mask:0xf bank_mask:0xf
	s_nop 1
	v_add_f32_dpp v66, v66, v66 row_ror:4 row_mask:0xf bank_mask:0xf
	s_nop 1
	v_add_f32_dpp v66, v66, v66 row_ror:2 row_mask:0xf bank_mask:0xf
	s_nop 1
	v_add_f32_dpp v66, v66, v66 row_ror:1 row_mask:0xf bank_mask:0xf
	v_max_f32_e32 v69, v69, v66
	s_waitcnt vmcnt(0)
	v_lshlrev_b32_e32 v67, 16, v62
	v_and_b32_e32 v68, 0xffff0000, v62
	v_mul_f32_e32 v66, v67, v67
	v_fmac_f32_e32 v66, v68, v68
	v_lshlrev_b32_e32 v67, 16, v63
	v_and_b32_e32 v68, 0xffff0000, v63
	v_fmac_f32_e32 v66, v67, v67
	v_fmac_f32_e32 v66, v68, v68
	v_lshlrev_b32_e32 v67, 16, v64
	v_and_b32_e32 v68, 0xffff0000, v64
	v_fmac_f32_e32 v66, v67, v67
	v_fmac_f32_e32 v66, v68, v68
	v_lshlrev_b32_e32 v67, 16, v65
	v_and_b32_e32 v68, 0xffff0000, v65
	v_fmac_f32_e32 v66, v67, v67
	v_fmac_f32_e32 v66, v68, v68
	s_nop 1
	v_add_f32_dpp v66, v66, v66 row_ror:8 row_mask:0xf bank_mask:0xf
	s_nop 1
	v_add_f32_dpp v66, v66, v66 row_ror:4 row_mask:0xf bank_mask:0xf
	s_nop 1
	v_add_f32_dpp v66, v66, v66 row_ror:2 row_mask:0xf bank_mask:0xf
	s_nop 1
	v_add_f32_dpp v66, v66, v66 row_ror:1 row_mask:0xf bank_mask:0xf
	v_max_f32_e32 v69, v69, v66
	s_nop 1
	v_readlane_b32 s89, v69, 0
	v_readlane_b32 s90, v69, 16
	v_readlane_b32 s91, v69, 32
	v_readlane_b32 s92, v69, 48
	s_max_u32 s89, s89, s90
	s_max_u32 s91, s91, s92
	s_max_u32 s89, s89, s91
	v_readfirstlane_b32 s90, v255
	s_lshr_b32 s90, s90, 8
	s_sub_i32 s91, s5, 8
	s_lshl_b32 s91, s91, 1
	s_add_i32 s91, s91, s90
	s_lshr_b32 s92, s4, 4
	s_lshl_b32 s92, s92, 4
	s_add_i32 s91, s91, s92
	s_lshl_b32 s91, s91, 2
	s_addk_i32 s91, 640
	s_add_u32 s92, s54, 0x80000
	s_addc_u32 s93, s55, 0
	s_mov_b64 s[94:95], exec
	s_mov_b64 exec, 1
	v_mov_b32_e32 v0, s91
	v_mov_b32_e32 v1, s89
	global_atomic_umax v0, v1, s[92:93]
	s_mov_b64 exec, s[94:95]
